# prompt attention: k/v rows of the workgroup's next item requested in the middle of the current item; stale vmcnt waits dropped
# speedup vs baseline: 1.0040x; 1.0006x over previous
; #define LAS __attribute__((address_space(3)))
; __device__ __forceinline__ void attn_prompt_item(LAS unsigned char* lds, const bf16_t* qkvb, bf16_t* og, float* lse, int it, int tid, int wave, int lane) {
;     const int b = it / 768, rem0 = it - b * 768, g = rem0 >> 8, rem = rem0 & 255, hh = rem & 3, rq = rem >> 2;
;     const int dl = 2 * g, dil = 1 << dl, r = rq & (dil - 1), qb = rq >> dl;
;     const float slope = exp2f(-8.0f * (float)(g * 4 + hh + 1) / 12.0f);
;     LAS bf16_t* Kl = (LAS bf16_t*)(lds + ATT_KL); LAS bf16_t* Vt = (LAS bf16_t*)(lds + ATT_VT); LAS bf16_t* Pw = (LAS bf16_t*)(lds + ATT_PW + wave * ATT_PW_WAVE);
;     const int colk = AW + g * 256 + hh * 64;
; #pragma unroll
;     for (int pp = 0; pp < 4; ++pp) {
;         const int p = tid + pp * NTHREADS, j = p >> 3, pc = p & 7, si = qb * 128 - 128 + j;
;         u32x4 kv = (u32x4){0u, 0u, 0u, 0u}, vv = (u32x4){0u, 0u, 0u, 0u};
;         if (si >= 0) { const bf16_t* kp = qkvb + (size_t)(b * SEQ + si * dil + r) * NQKV + colk + pc * 8; kv = *(const u32x4*)kp; vv = *(const u32x4*)(kp + AW); }
;         *(LAS u32x4*)(Kl + j * KL_PITCH + pc * 8) = kv;
;         LAS bf16_t* vd = Vt + (pc * 8) * VT_PITCH + ((((j >> 3) ^ pc) << 3) | (j & 7));
;         vd[0 * VT_PITCH] = (bf16_t)(vv.x & 0xffffu); vd[1 * VT_PITCH] = (bf16_t)(vv.x >> 16); vd[2 * VT_PITCH] = (bf16_t)(vv.y & 0xffffu); vd[3 * VT_PITCH] = (bf16_t)(vv.y >> 16);
;         vd[4 * VT_PITCH] = (bf16_t)(vv.z & 0xffffu); vd[5 * VT_PITCH] = (bf16_t)(vv.z >> 16); vd[6 * VT_PITCH] = (bf16_t)(vv.w & 0xffffu); vd[7 * VT_PITCH] = (bf16_t)(vv.w >> 16);
;     }
;     { const int d = tid >> 3, blk = 32 + (tid & 7); *(LAS u32x4*)(Vt + d * VT_PITCH + blk * 8) = (u32x4){0u, 0u, 0u, 0u}; }
;     const int ql = lane & 15, fq = lane >> 4;
;     const size_t qrow = (size_t)b * SEQ + (size_t)(qb * 128 + 16 * wave + ql) * dil + r;
;     const bf16_t* qp = qkvb + qrow * NQKV + g * 256 + hh * 64;
;     const bf16x8 q0 = *(const bf16x8*)(qp + 8 * fq), q1 = *(const bf16x8*)(qp + 32 + 8 * fq);
.LBB0_630:
	s_or_b64 exec, exec, s[28:29]
	s_load_dwordx2 s[6:7], s[0:1], 0xd0
	s_waitcnt lgkmcnt(0)
	s_barrier
	s_load_dwordx2 s[40:41], s[0:1], 0xc8
	s_add_u32 s34, s6, 0x108e0000
	s_addc_u32 s35, s7, 0
	s_add_u32 s38, s6, 0x139a0000
	v_lshrrev_b32_e32 v153, 4, v192
	s_addc_u32 s39, s7, 0
	s_lshl_b32 s69, s42, 4
	v_lshlrev_b32_e32 v150, 2, v153
	s_cmpk_gt_i32 s2, 0x5ff
	v_lshlrev_b32_e32 v154, 3, v153
	v_mov_b32_e32 v13, 0
	v_or_b32_e32 v151, 2, v150
	v_or_b32_e32 v152, 3, v150
	s_cbranch_scc1 .LBB0_640
	v_or_b32_e32 v0, 0x80, v161
	v_readlane_b32 s28, v243, 3
	v_or_b32_e32 v19, 0x81, v150
	s_mul_i32 s4, s28, 0x1500
	v_sub_u32_e32 v92, v0, v19
	v_or_b32_e32 v19, 0x82, v150
	v_or_b32_e32 v35, 16, v150
	v_or_b32_e32 v37, 17, v150
	v_or_b32_e32 v39, 18, v150
	v_or_b32_e32 v41, 19, v150
	v_or_b32_e32 v43, 32, v150
	v_or_b32_e32 v45, 33, v150
	v_or_b32_e32 v47, 34, v150
	v_or_b32_e32 v49, 35, v150
	v_or_b32_e32 v51, 48, v150
	v_or_b32_e32 v53, 49, v150
	v_or_b32_e32 v55, 50, v150
	v_or_b32_e32 v57, 51, v150
	v_or_b32_e32 v59, 64, v150
	v_or_b32_e32 v61, 0x41, v150
	v_or_b32_e32 v63, 0x42, v150
	v_or_b32_e32 v65, 0x43, v150
	v_or_b32_e32 v67, 0x50, v150
	v_or_b32_e32 v69, 0x51, v150
	v_or_b32_e32 v71, 0x52, v150
	v_or_b32_e32 v73, 0x53, v150
	v_or_b32_e32 v75, 0x60, v150
	v_or_b32_e32 v77, 0x61, v150
	v_or_b32_e32 v79, 0x62, v150
	v_or_b32_e32 v81, 0x63, v150
	v_or_b32_e32 v83, 0x70, v150
	v_or_b32_e32 v85, 0x71, v150
	v_or_b32_e32 v87, 0x72, v150
	v_or_b32_e32 v89, 0x73, v150
	v_sub_u32_e32 v93, v0, v19
	v_or_b32_e32 v19, 0x83, v150
	s_add_i32 s4, s4, 0
	v_sub_u32_e32 v31, v0, v150
	v_xad_u32 v32, v150, -1, v0
	v_sub_u32_e32 v33, v0, v151
	v_sub_u32_e32 v34, v0, v152
	v_sub_u32_e32 v36, v0, v35
	v_sub_u32_e32 v38, v0, v37
	v_sub_u32_e32 v40, v0, v39
	v_sub_u32_e32 v42, v0, v41
	v_sub_u32_e32 v44, v0, v43
	v_sub_u32_e32 v46, v0, v45
	v_sub_u32_e32 v48, v0, v47
	v_sub_u32_e32 v50, v0, v49
	v_sub_u32_e32 v52, v0, v51
	v_sub_u32_e32 v54, v0, v53
	v_sub_u32_e32 v56, v0, v55
	v_sub_u32_e32 v58, v0, v57
	v_sub_u32_e32 v60, v0, v59
	v_sub_u32_e32 v62, v0, v61
	v_sub_u32_e32 v64, v0, v63
	v_sub_u32_e32 v66, v0, v65
	v_sub_u32_e32 v68, v0, v67
	v_sub_u32_e32 v70, v0, v69
	v_sub_u32_e32 v72, v0, v71
	v_sub_u32_e32 v74, v0, v73
	v_sub_u32_e32 v76, v0, v75
	v_sub_u32_e32 v78, v0, v77
	v_sub_u32_e32 v80, v0, v79
	v_sub_u32_e32 v82, v0, v81
	v_sub_u32_e32 v84, v0, v83
	v_sub_u32_e32 v86, v0, v85
	v_sub_u32_e32 v88, v0, v87
	v_sub_u32_e32 v90, v0, v89
	v_add_u32_e32 v18, s69, v0
	v_sub_u32_e32 v94, v0, v19
	s_add_i32 s4, s4, 0x13400
	v_mul_u32_u24_e32 v0, 0x150, v161
	v_and_b32_e32 v1, 7, v160
	v_add3_u32 v95, s4, v0, v154
	v_lshl_add_u32 v0, s28, 1, v153
	v_lshlrev_b32_e32 v12, 4, v1
	v_lshrrev_b32_e32 v4, 6, v160
	v_lshrrev_b32_e32 v19, 3, v161
	v_add_u32_e32 v96, 4, v0
	v_add_u32_e32 v2, 0, v12
	s_movk_i32 s6, 0x1470
	v_bitop3_b32 v4, v4, v160, 7 bitop3:0x78
	v_lshrrev_b32_e32 v5, 2, v160
	v_xor_b32_e32 v97, v96, v19
	v_mad_u32_u24 v1, v1, s6, v2
	v_lshlrev_b32_e32 v4, 4, v4
	v_and_b32_e32 v5, 14, v5
	v_lshlrev_b32_e32 v112, 4, v97
	v_add_u32_e32 v97, 8, v0
	v_add3_u32 v23, v1, v4, v5
	v_add_u32_e32 v4, 0x200, v160
	v_xor_b32_e32 v98, v97, v19
	v_lshrrev_b32_e32 v24, 3, v4
	v_lshrrev_b32_e32 v4, 6, v4
	v_lshlrev_b32_e32 v113, 4, v98
	v_add_u32_e32 v98, 12, v0
	v_bitop3_b32 v4, v4, v160, 7 bitop3:0x78
	v_xor_b32_e32 v99, v98, v19
	v_lshlrev_b32_e32 v4, 4, v4
	v_lshlrev_b32_e32 v114, 4, v99
	v_add_u32_e32 v99, 16, v0
	v_add3_u32 v25, v1, v4, v5
	v_or_b32_e32 v4, 0x400, v160
	v_xor_b32_e32 v100, v99, v19
	v_lshrrev_b32_e32 v26, 3, v4
	v_lshrrev_b32_e32 v4, 6, v4
	v_lshlrev_b32_e32 v115, 4, v100
	v_bitop3_b32 v100, v0, v19, 2 bitop3:0x1e
	v_bitop3_b32 v4, v4, v160, 7 bitop3:0x78
	v_lshlrev_b32_e32 v116, 4, v100
	v_bitop3_b32 v100, v96, v19, 2 bitop3:0x1e
	v_lshlrev_b32_e32 v4, 4, v4
	v_lshlrev_b32_e32 v117, 4, v100
	v_bitop3_b32 v100, v97, v19, 2 bitop3:0x1e
	v_add3_u32 v27, v1, v4, v5
	v_add_u32_e32 v4, 0x600, v160
	v_lshlrev_b32_e32 v118, 4, v100
; __device__ __forceinline__ void attn_prompt_item(LAS unsigned char* lds, const bf16_t* qkvb, bf16_t* og, float* lse, int it, int tid, int wave, int lane) {
;     ...
;     LAS bf16_t* Kl = (LAS bf16_t*)(lds + ATT_KL); LAS bf16_t* Vt = (LAS bf16_t*)(lds + ATT_VT); LAS bf16_t* Pw = (LAS bf16_t*)(lds + ATT_PW + wave * ATT_PW_WAVE);
;     const int colk = AW + g * 256 + hh * 64;
; #pragma unroll
;     for (int pp = 0; pp < 4; ++pp) {
;         const int p = tid + pp * NTHREADS, j = p >> 3, pc = p & 7, si = qb * 128 - 128 + j;
;         u32x4 kv = (u32x4){0u, 0u, 0u, 0u}, vv = (u32x4){0u, 0u, 0u, 0u};
;         if (si >= 0) { const bf16_t* kp = qkvb + (size_t)(b * SEQ + si * dil + r) * NQKV + colk + pc * 8; kv = *(const u32x4*)kp; vv = *(const u32x4*)(kp + AW); }
;         *(LAS u32x4*)(Kl + j * KL_PITCH + pc * 8) = kv;
;         LAS bf16_t* vd = Vt + (pc * 8) * VT_PITCH + ((((j >> 3) ^ pc) << 3) | (j & 7));
;         vd[0 * VT_PITCH] = (bf16_t)(vv.x & 0xffffu); vd[1 * VT_PITCH] = (bf16_t)(vv.x >> 16); vd[2 * VT_PITCH] = (bf16_t)(vv.y & 0xffffu); vd[3 * VT_PITCH] = (bf16_t)(vv.y >> 16);
;         vd[4 * VT_PITCH] = (bf16_t)(vv.z & 0xffffu); vd[5 * VT_PITCH] = (bf16_t)(vv.z >> 16); vd[6 * VT_PITCH] = (bf16_t)(vv.w & 0xffffu); vd[7 * VT_PITCH] = (bf16_t)(vv.w >> 16);
;     }
;     { const int d = tid >> 3, blk = 32 + (tid & 7); *(LAS u32x4*)(Vt + d * VT_PITCH + blk * 8) = (u32x4){0u, 0u, 0u, 0u}; }
;     const int ql = lane & 15, fq = lane >> 4;
;     const size_t qrow = (size_t)b * SEQ + (size_t)(qb * 128 + 16 * wave + ql) * dil + r;
;     const bf16_t* qp = qkvb + qrow * NQKV + g * 256 + hh * 64;
;     const bf16x8 q0 = *(const bf16x8*)(qp + 8 * fq), q1 = *(const bf16x8*)(qp + 32 + 8 * fq);
;     __syncthreads();
;     f32x4 sc[9]; float mx = -1e30f;
; #pragma unroll
;     for (int T = 0; T < 9; ++T) {
;         const LAS bf16_t* kr = Kl + (16 * (wave + T) + ql) * KL_PITCH + 8 * fq;
;         const bf16x8 a0 = *(const LAS bf16x8*)kr, a1 = *(const LAS bf16x8*)(kr + 32);
;         f32x4 acc = (f32x4){0.f, 0.f, 0.f, 0.f};
;         acc = __builtin_amdgcn_mfma_f32_16x16x32_bf16(a0, q0, acc, 0, 0, 0);
;         acc = __builtin_amdgcn_mfma_f32_16x16x32_bf16(a1, q1, acc, 0, 0, 0);
; #pragma unroll
;         for (int j = 0; j < 4; ++j) {
;             const int krel = 16 * T + 4 * fq + j, delta = 128 + ql - krel, ksub = qb * 128 - 128 + 16 * wave + krel;
	v_bitop3_b32 v100, v98, v19, 2 bitop3:0x1e
	v_lshrrev_b32_e32 v28, 3, v4
	v_lshrrev_b32_e32 v4, 6, v4
	v_lshlrev_b32_e32 v119, 4, v100
	v_bitop3_b32 v100, v99, v19, 2 bitop3:0x1e
	v_bitop3_b32 v4, v4, v160, 7 bitop3:0x78
	v_lshlrev_b32_e32 v120, 4, v100
	v_bitop3_b32 v100, v0, v19, 4 bitop3:0x1e
	v_lshrrev_b32_e32 v22, 3, v160
	v_lshlrev_b32_e32 v4, 4, v4
	v_lshlrev_b32_e32 v121, 4, v100
	v_bitop3_b32 v100, v96, v19, 4 bitop3:0x1e
	v_bitop3_b32 v96, v96, v19, 6 bitop3:0x1e
	v_add3_u32 v29, v1, v4, v5
	v_mul_u32_u24_e32 v1, 0x290, v22
	v_lshlrev_b32_e32 v122, 4, v100
	v_bitop3_b32 v100, v97, v19, 4 bitop3:0x1e
	v_lshlrev_b32_e32 v127, 4, v96
	v_bitop3_b32 v96, v97, v19, 6 bitop3:0x1e
	v_mbcnt_hi_u32_b32 v97, -1, v193
	v_add3_u32 v30, 0, v1, v130
	v_lshlrev_b32_e32 v123, 4, v100
	v_bitop3_b32 v100, v98, v19, 4 bitop3:0x1e
	v_lshlrev_b32_e32 v130, 4, v96
	v_bitop3_b32 v96, v98, v19, 6 bitop3:0x1e
	v_and_b32_e32 v98, 64, v97
	v_lshlrev_b32_e32 v131, 4, v96
	v_xor_b32_e32 v96, 16, v97
	v_add_u32_e32 v98, 64, v98
	s_movk_i32 s6, 0x90
	v_add_u32_e32 v5, s69, v161
	v_xor_b32_e32 v21, v0, v19
	v_lshlrev_b32_e32 v124, 4, v100
	v_bitop3_b32 v100, v99, v19, 4 bitop3:0x1e
	v_bitop3_b32 v0, v0, v19, 6 bitop3:0x1e
	v_bitop3_b32 v19, v99, v19, 6 bitop3:0x1e
	v_cmp_lt_i32_e32 vcc, v96, v98
	v_xor_b32_e32 v99, 32, v97
	s_movk_i32 s7, 0x290
	v_or_b32_e32 v4, s69, v161
	v_mul_lo_u32 v5, v5, s6
	v_lshlrev_b32_e32 v125, 4, v100
	v_or_b32_e32 v100, 48, v192
	v_cndmask_b32_e32 v96, v97, v96, vcc
	v_cmp_lt_i32_e32 vcc, v99, v98
	v_lshl_add_u64 v[14:15], s[24:25], 0, v[12:13]
	v_mul_u32_u24_e32 v3, 0x90, v22
	v_mul_u32_u24_e32 v6, 0x90, v24
	v_mul_u32_u24_e32 v7, 0x90, v26
	v_mul_u32_u24_e32 v8, 0x90, v28
	v_lshl_add_u32 v1, v154, 1, 0
	v_mul_lo_u32 v4, v4, s6
	s_movk_i32 s26, 0x81
	v_add_u32_e32 v9, 0x900, v5
	v_add_u32_e32 v10, 0x1200, v5
	v_add_u32_e32 v11, 0x1b00, v5
	v_add_u32_e32 v12, 0x2400, v5
	v_add_u32_e32 v16, 0x2d00, v5
	v_add_u32_e32 v17, 0x3600, v5
	v_add_u32_e32 v5, 0x3f00, v5
	v_mul_lo_u32 v18, v18, s6
	v_sub_u32_e32 v91, v161, v150
	v_mad_u32_u24 v20, v161, s7, 0
	v_lshlrev_b32_e32 v21, 4, v21
	v_mad_u32_u24 v132, v100, s7, 0
	v_lshlrev_b32_e32 v0, 4, v0
	v_lshlrev_b32_e32 v19, 4, v19
	v_cndmask_b32_e32 v97, v97, v99, vcc
	s_mov_b32 s29, 0
	s_movk_i32 s27, 0x600
	v_cmp_gt_u32_e64 s[46:47], s26, v31
	v_cmp_gt_u32_e64 s[48:49], s26, v32
	v_cmp_gt_u32_e64 s[50:51], s26, v33
	v_cmp_gt_u32_e64 s[52:53], s26, v34
	s_movk_i32 s42, 0x1200
	v_cmp_gt_u32_e64 s[54:55], s26, v91
	v_cmp_gt_u32_e64 s[56:57], s26, v92
	v_cmp_gt_u32_e64 s[58:59], s26, v93
	v_cmp_gt_u32_e64 s[60:61], s26, v94
	v_lshlrev_b32_e32 v96, 2, v96
	v_lshlrev_b32_e32 v97, 2, v97
	v_add_u32_e32 v98, v2, v3
	s_mov_b32 s43, 0x41400000
	v_add_u32_e32 v99, v2, v6
	v_add_u32_e32 v100, v2, v7
	v_add_u32_e32 v101, v2, v8
	v_add_u32_e32 v102, v1, v4
	v_add_u32_e32 v103, v1, v9
	v_add_u32_e32 v104, v1, v10
	v_add_u32_e32 v105, v1, v11
	v_add_u32_e32 v106, v1, v12
	v_add_u32_e32 v107, v1, v16
	v_add_u32_e32 v108, v1, v17
	v_add_u32_e32 v109, v1, v5
	v_add_u32_e32 v110, v1, v18
	s_mov_b32 s67, 0xefa18f08
	v_add_u32_e32 v111, v20, v21
	v_add_u32_e32 v112, v20, v112
	v_add_u32_e32 v113, v20, v113
	v_add_u32_e32 v114, v20, v114
	v_add_u32_e32 v115, v20, v115
	v_add_u32_e32 v116, v20, v116
	v_add_u32_e32 v117, v20, v117
	v_add_u32_e32 v118, v20, v118
	v_add_u32_e32 v119, v20, v119
	v_add_u32_e32 v120, v20, v120
	v_add_u32_e32 v121, v20, v121
	v_add_u32_e32 v122, v20, v122
	v_add_u32_e32 v123, v20, v123
	v_add_u32_e32 v124, v20, v124
	v_add_u32_e32 v125, v20, v125
	v_add_u32_e32 v126, v132, v0
	v_add_u32_e32 v127, v132, v127
	v_add_u32_e32 v130, v132, v130
	v_add_u32_e32 v131, v132, v131
	v_add_u32_e32 v132, v132, v19
	v_mov_b32_e32 v133, 0x42800000
	v_mov_b32_e32 v174, v13
	v_mov_b32_e32 v175, v13
	v_mov_b32_e32 v176, v13
	v_mov_b32_e32 v177, v13
	v_mov_b32_e32 v16, 0x3e000000
	v_mov_b32_e32 v134, 0xf149f2ca
	v_mov_b32_e32 v135, 0x41b17218
	s_mov_b32 s76, s2
	s_mov_b32 s45, 0
	s_branch .LBB0_633

; #define LAS __attribute__((address_space(3)))
; __device__ __forceinline__ void attn_prompt_item(LAS unsigned char* lds, const bf16_t* qkvb, bf16_t* og, float* lse, int it, int tid, int wave, int lane) {
;     const int b = it / 768, rem0 = it - b * 768, g = rem0 >> 8, rem = rem0 & 255, hh = rem & 3, rq = rem >> 2;
;     const int dl = 2 * g, dil = 1 << dl, r = rq & (dil - 1), qb = rq >> dl;
;     const float slope = exp2f(-8.0f * (float)(g * 4 + hh + 1) / 12.0f);
;     LAS bf16_t* Kl = (LAS bf16_t*)(lds + ATT_KL); LAS bf16_t* Vt = (LAS bf16_t*)(lds + ATT_VT); LAS bf16_t* Pw = (LAS bf16_t*)(lds + ATT_PW + wave * ATT_PW_WAVE);
;     const int colk = AW + g * 256 + hh * 64;
; #pragma unroll
;     for (int pp = 0; pp < 4; ++pp) {
;         const int p = tid + pp * NTHREADS, j = p >> 3, pc = p & 7, si = qb * 128 - 128 + j;
;         u32x4 kv = (u32x4){0u, 0u, 0u, 0u}, vv = (u32x4){0u, 0u, 0u, 0u};
;         if (si >= 0) { const bf16_t* kp = qkvb + (size_t)(b * SEQ + si * dil + r) * NQKV + colk + pc * 8; kv = *(const u32x4*)kp; vv = *(const u32x4*)(kp + AW); }
.LBB0_633:
	s_mul_hi_i32 s4, s76, 0x2aaaaaab
	s_lshr_b32 s6, s4, 31
	s_lshr_b32 s4, s4, 8
	s_add_i32 s4, s4, s6
	s_mulk_i32 s4, 0x600
	s_sub_i32 s4, s76, s4
	s_mul_i32 s6, s4, 0x2aab
	s_lshr_b32 s7, s6, 31
	s_ashr_i32 s30, s6, 23
	s_add_i32 s30, s30, s7
	s_mul_i32 s6, s30, 0xfffffd00
	s_add_i32 s6, s6, s4
	s_ashr_i32 s37, s6, 8
	s_and_b32 s77, s4, 3
	s_bfe_u32 s7, s4, 0x60002
	s_lshl_b32 s4, s37, 1
	s_lshl_b32 s26, -1, s4
	s_lshr_b32 s68, s7, s4
	s_and_b32 s80, s6, 0xffffff00
	s_andn2_b32 s28, s7, s26
	s_lshl_b32 s26, s77, 6
	s_lshl_b32 s31, s68, 7
	s_lshl_b32 s6, s30, 13
	s_ashr_i32 s81, s80, 31
	s_add_i32 s33, s31, 0xffffff80
	s_or_b32 s36, s28, s6
	s_or_b32 s6, s80, s26
	s_mov_b32 s7, s81
	s_cmp_eq_u32 s68, 0
	v_lshl_add_u64 v[8:9], s[6:7], 1, v[14:15]
	s_cbranch_scc1 .Lattp_zero01
	s_cmp_eq_u32 s45, 1
	s_cbranch_scc1 .Lattp_ld23x
	v_or_b32_e32 v200, s33, v22
	v_lshlrev_b32_e32 v200, s4, v200
	v_add_u32_e32 v200, s36, v200
	v_mad_i64_i32 v[200:201], s[6:7], v200, s42, v[8:9]
	global_load_dwordx4 v[206:209], v[200:201], off offset:1536
	global_load_dwordx4 v[210:213], v[200:201], off offset:3072
	v_add_u32_e32 v202, s33, v24
	v_lshlrev_b32_e32 v202, s4, v202
	v_add_u32_e32 v202, s36, v202
	v_mad_i64_i32 v[202:203], s[6:7], v202, s42, v[8:9]
	global_load_dwordx4 v[214:217], v[202:203], off offset:1536
	global_load_dwordx4 v[218:221], v[202:203], off offset:3072
	s_branch .Lattp_ld23

; #define LAS __attribute__((address_space(3)))
; __device__ __forceinline__ void attn_prompt_item(LAS unsigned char* lds, const bf16_t* qkvb, bf16_t* og, float* lse, int it, int tid, int wave, int lane) {
;     ...
; #pragma unroll
;     for (int pp = 0; pp < 4; ++pp) {
;         const int p = tid + pp * NTHREADS, j = p >> 3, pc = p & 7, si = qb * 128 - 128 + j;
;         u32x4 kv = (u32x4){0u, 0u, 0u, 0u}, vv = (u32x4){0u, 0u, 0u, 0u};
;         if (si >= 0) { const bf16_t* kp = qkvb + (size_t)(b * SEQ + si * dil + r) * NQKV + colk + pc * 8; kv = *(const u32x4*)kp; vv = *(const u32x4*)(kp + AW); }
;         *(LAS u32x4*)(Kl + j * KL_PITCH + pc * 8) = kv;
;         LAS bf16_t* vd = Vt + (pc * 8) * VT_PITCH + ((((j >> 3) ^ pc) << 3) | (j & 7));
;         vd[0 * VT_PITCH] = (bf16_t)(vv.x & 0xffffu); vd[1 * VT_PITCH] = (bf16_t)(vv.x >> 16); vd[2 * VT_PITCH] = (bf16_t)(vv.y & 0xffffu); vd[3 * VT_PITCH] = (bf16_t)(vv.y >> 16);
;         vd[4 * VT_PITCH] = (bf16_t)(vv.z & 0xffffu); vd[5 * VT_PITCH] = (bf16_t)(vv.z >> 16); vd[6 * VT_PITCH] = (bf16_t)(vv.w & 0xffffu); vd[7 * VT_PITCH] = (bf16_t)(vv.w >> 16);
;     }
;     { const int d = tid >> 3, blk = 32 + (tid & 7); *(LAS u32x4*)(Vt + d * VT_PITCH + blk * 8) = (u32x4){0u, 0u, 0u, 0u}; }
;     const int ql = lane & 15, fq = lane >> 4;
;     const size_t qrow = (size_t)b * SEQ + (size_t)(qb * 128 + 16 * wave + ql) * dil + r;
;     const bf16_t* qp = qkvb + qrow * NQKV + g * 256 + hh * 64;
;     const bf16x8 q0 = *(const bf16x8*)(qp + 8 * fq), q1 = *(const bf16x8*)(qp + 32 + 8 * fq);
.Lattp_ld23:
	s_cmp_eq_u32 s45, 1
	s_cbranch_scc1 .Lattp_ld23x
	v_add_u32_e32 v196, s33, v26
	v_lshlrev_b32_e32 v196, s4, v196
	v_add_u32_e32 v196, s36, v196
	v_mad_i64_i32 v[196:197], s[6:7], v196, s42, v[8:9]
	global_load_dwordx4 v[222:225], v[196:197], off offset:1536
	global_load_dwordx4 v[226:229], v[196:197], off offset:3072
	v_add_u32_e32 v198, s33, v28
	v_lshlrev_b32_e32 v198, s4, v198
	v_add_u32_e32 v198, s36, v198
	v_mad_i64_i32 v[198:199], s[6:7], v198, s42, v[8:9]
	global_load_dwordx4 v[230:233], v[198:199], off offset:1536
	global_load_dwordx4 v[234:237], v[198:199], off offset:3072
.Lattp_ld23x:
	s_mov_b32 s45, 0
	s_add_i32 s98, s31, s69
	v_or_b32_e32 v252, s98, v161
	v_mov_b32_e32 v253, 0
	v_lshlrev_b64 v[252:253], s4, v[252:253]
	s_sext_i32_i16 s98, s30
	s_ashr_i32 s99, s98, 31
	s_lshl_b64 s[98:99], s[98:99], 13
	s_or_b32 s98, s98, s28
	v_lshl_add_u64 v[254:255], s[98:99], 0, v[252:253]
	v_mov_b64_e32 v[252:253], s[24:25]
	v_mad_u64_u32 v[252:253], s[100:101], v254, s42, v[252:253]
	v_mov_b32_e32 v246, v253
	v_mad_u64_u32 v[246:247], s[100:101], v255, s42, v[246:247]
	v_mov_b32_e32 v253, v246
	s_lshl_b64 s[98:99], s[80:81], 1
	v_lshl_add_u64 v[252:253], v[252:253], 0, s[98:99]
	s_lshl_b32 s98, s26, 1
	s_mov_b32 s99, 0
	v_lshl_add_u64 v[252:253], v[252:253], 0, s[98:99]
	v_lshlrev_b32_e32 v254, 1, v154
	v_mov_b32_e32 v255, 0
	v_lshl_add_u64 v[252:253], v[252:253], 0, v[254:255]
	global_load_dwordx4 v[244:247], v[252:253], off
	global_load_dwordx4 v[248:251], v[252:253], off offset:64
	s_waitcnt vmcnt(9)
	ds_write_b128 v98, v[206:209]
	s_waitcnt vmcnt(8)
	ds_write_b16 v23, v210 offset:36864
	ds_write_b16_d16_hi v23, v210 offset:37520
	ds_write_b16 v23, v211 offset:38176
	ds_write_b16_d16_hi v23, v211 offset:38832
	ds_write_b16 v23, v212 offset:39488
	ds_write_b16_d16_hi v23, v212 offset:40144
	ds_write_b16 v23, v213 offset:40800
	ds_write_b16_d16_hi v23, v213 offset:41456
	s_lshl_b32 s78, s37, 2
	s_waitcnt vmcnt(7)
	ds_write_b128 v99, v[214:217]
	s_waitcnt vmcnt(6)
	ds_write_b16 v25, v218 offset:36864
	ds_write_b16_d16_hi v25, v218 offset:37520
	ds_write_b16 v25, v219 offset:38176
	ds_write_b16_d16_hi v25, v219 offset:38832
	ds_write_b16 v25, v220 offset:39488
	ds_write_b16_d16_hi v25, v220 offset:40144
	ds_write_b16 v25, v221 offset:40800
	ds_write_b16_d16_hi v25, v221 offset:41456
	s_or_b32 s6, s77, s78
	s_add_i32 s6, s6, 1
	v_cvt_f32_i32_e32 v10, s6
	v_mul_f32_e32 v10, 0xc1000000, v10
	v_div_scale_f32 v11, s[6:7], s43, s43, v10
	v_rcp_f32_e32 v12, v11
	s_waitcnt vmcnt(5)
	ds_write_b128 v100, v[222:225]
	v_fma_f32 v17, -v11, v12, 1.0
	v_fmac_f32_e32 v12, v17, v12
	v_div_scale_f32 v17, vcc, v10, s43, v10
	v_mul_f32_e32 v18, v17, v12
	v_fma_f32 v19, -v11, v18, v17
	v_fmac_f32_e32 v18, v19, v12
	v_fma_f32 v11, -v11, v18, v17
	v_div_fmas_f32 v11, v11, v12, v18
	v_div_fixup_f32 v10, v11, s43, v10
	s_waitcnt vmcnt(4)
	ds_write_b16 v27, v226 offset:36864
	ds_write_b16_d16_hi v27, v226 offset:37520
	ds_write_b16 v27, v227 offset:38176
	ds_write_b16_d16_hi v27, v227 offset:38832
	ds_write_b16 v27, v228 offset:39488
	ds_write_b16_d16_hi v27, v228 offset:40144
	ds_write_b16 v27, v229 offset:40800
	ds_write_b16_d16_hi v27, v229 offset:41456
	s_mov_b32 s6, 0xc2fc0000
	v_cmp_gt_f32_e32 vcc, s6, v10
	s_and_b64 s[6:7], vcc, exec
	s_cselect_b32 s6, 0xffffffc0, 0
	s_add_i32 s31, s31, s69
	v_or_b32_e32 v12, s31, v161
	s_lshl_b64 s[80:81], s[80:81], 1
	s_waitcnt vmcnt(3)
	ds_write_b128 v101, v[230:233]
	s_waitcnt vmcnt(2)
	ds_write_b16 v29, v234 offset:36864
	ds_write_b16_d16_hi v29, v234 offset:37520
	ds_write_b16 v29, v235 offset:38176
	ds_write_b16_d16_hi v29, v235 offset:38832
	ds_write_b16 v29, v236 offset:39488
	ds_write_b16_d16_hi v29, v236 offset:40144
	ds_write_b16 v29, v237 offset:40800
	ds_write_b16_d16_hi v29, v237 offset:41456
	v_cndmask_b32_e32 v0, 0, v133, vcc
	v_add_f32_e32 v0, v10, v0
	v_exp_f32_e32 v0, v0
	ds_write_b128 v30, v[174:177] offset:37376
	v_ldexp_f32 v21, v0, s6
	s_sext_i32_i16 s6, s30
	s_ashr_i32 s7, s6, 31
	s_lshl_b64 s[6:7], s[6:7], 13
	v_lshlrev_b64 v[0:1], s4, v[12:13]
	s_or_b32 s6, s6, s28
	v_lshl_add_u64 v[18:19], s[6:7], 0, v[0:1]
	v_mov_b64_e32 v[0:1], s[24:25]
	v_mad_u64_u32 v[0:1], s[6:7], v18, s42, v[0:1]
	v_mov_b32_e32 v2, v1
	v_mad_u64_u32 v[2:3], s[6:7], v19, s42, v[2:3]
	v_mov_b32_e32 v1, v2
	v_lshl_add_u64 v[0:1], v[0:1], 0, s[80:81]
	s_lshl_b32 s28, s26, 1
	v_lshl_add_u64 v[0:1], v[0:1], 0, s[28:29]
	v_lshlrev_b32_e32 v12, 1, v154
	v_lshl_add_u64 v[4:5], v[0:1], 0, v[12:13]
	s_waitcnt vmcnt(0)
	v_mov_b32_e32 v0, v244
	v_mov_b32_e32 v1, v245
	v_mov_b32_e32 v2, v246
	v_mov_b32_e32 v3, v247
	v_mov_b32_e32 v4, v248
	v_mov_b32_e32 v5, v249
	v_mov_b32_e32 v6, v250
	v_mov_b32_e32 v7, v251
	s_mov_b32 s45, 0
	s_add_i32 s98, s76, s66
	s_cmpk_gt_i32 s98, 0x5ff
	s_cbranch_scc1 .Lattp_nopf
	s_mul_i32 s99, s98, 0x2aab
	s_lshr_b32 s99, s99, 23
	s_mul_i32 s32, s99, 0xfffffd00
	s_add_i32 s32, s32, s98
	s_ashr_i32 s40, s32, 8
	s_bfe_u32 s41, s98, 0x60002
	s_lshl_b32 s44, s40, 1
	s_lshl_b32 s40, -1, s44
	s_lshr_b32 s82, s41, s44
	s_andn2_b32 s41, s41, s40
	s_and_b32 s32, s32, 0xffffff00
	s_and_b32 s40, s98, 3
	s_lshl_b32 s40, s40, 6
	s_or_b32 s98, s32, s40
	s_lshl_b32 s40, s82, 7
	s_add_i32 s40, s40, 0xffffff80
	s_lshl_b32 s99, s99, 13
	s_or_b32 s41, s41, s99
	s_mov_b32 s99, 0
	v_lshl_add_u64 v[238:239], s[98:99], 1, v[14:15]
	s_cmp_eq_u32 s82, 0
	s_cbranch_scc1 .Lattp_pf23
	v_or_b32_e32 v200, s40, v22
	v_lshlrev_b32_e32 v200, s44, v200
	v_add_u32_e32 v200, s41, v200
	v_mad_i64_i32 v[200:201], s[100:101], v200, s42, v[238:239]
	global_load_dwordx4 v[206:209], v[200:201], off offset:1536
	global_load_dwordx4 v[210:213], v[200:201], off offset:3072
	v_add_u32_e32 v202, s40, v24
	v_lshlrev_b32_e32 v202, s44, v202
	v_add_u32_e32 v202, s41, v202
	v_mad_i64_i32 v[202:203], s[100:101], v202, s42, v[238:239]
	global_load_dwordx4 v[214:217], v[202:203], off offset:1536
	global_load_dwordx4 v[218:221], v[202:203], off offset:3072
; #define LAS __attribute__((address_space(3)))
; __device__ __forceinline__ void attn_prompt_item(LAS unsigned char* lds, const bf16_t* qkvb, bf16_t* og, float* lse, int it, int tid, int wave, int lane) {
;     ...
;     __syncthreads();
;     f32x4 sc[9]; float mx = -1e30f;
; #pragma unroll
;     for (int T = 0; T < 9; ++T) {
;         const LAS bf16_t* kr = Kl + (16 * (wave + T) + ql) * KL_PITCH + 8 * fq;
;         const bf16x8 a0 = *(const LAS bf16x8*)kr, a1 = *(const LAS bf16x8*)(kr + 32);
;         f32x4 acc = (f32x4){0.f, 0.f, 0.f, 0.f};
;         acc = __builtin_amdgcn_mfma_f32_16x16x32_bf16(a0, q0, acc, 0, 0, 0);
;         acc = __builtin_amdgcn_mfma_f32_16x16x32_bf16(a1, q1, acc, 0, 0, 0);
; #pragma unroll
;         for (int j = 0; j < 4; ++j) {
;             const int krel = 16 * T + 4 * fq + j, delta = 128 + ql - krel, ksub = qb * 128 - 128 + 16 * wave + krel;
;             const bool valid = (delta >= 0) && (delta <= 128) && (ksub >= 0);
;             const float s = valid ? acc[j] * 0.125f - slope * (float)(delta * dil) : -1e30f;
;             acc[j] = s; mx = fmaxf(mx, s); }
;         sc[T] = acc;
;     }
.Lattp_pf23:
	v_add_u32_e32 v196, s40, v26
	v_lshlrev_b32_e32 v196, s44, v196
	v_add_u32_e32 v196, s41, v196
	v_mad_i64_i32 v[196:197], s[100:101], v196, s42, v[238:239]
	global_load_dwordx4 v[222:225], v[196:197], off offset:1536
	global_load_dwordx4 v[226:229], v[196:197], off offset:3072
	v_add_u32_e32 v198, s40, v28
	v_lshlrev_b32_e32 v198, s44, v198
	v_add_u32_e32 v198, s41, v198
	v_mad_i64_i32 v[198:199], s[100:101], v198, s42, v[238:239]
	global_load_dwordx4 v[230:233], v[198:199], off offset:1536
	global_load_dwordx4 v[234:237], v[198:199], off offset:3072
	s_mov_b32 s45, 1
.Lattp_nopf:
	s_waitcnt lgkmcnt(0)
	s_barrier
	ds_read_b128 v[8:11], v102
	ds_read_b128 v[136:139], v102 offset:64
	v_lshlrev_b32_e32 v12, s4, v31
	v_cvt_f32_u32_e32 v17, v12
	s_sub_i32 s26, 0x7f, s31
	v_cmp_lt_i32_e32 vcc, s26, v150
	s_and_b64 vcc, s[46:47], vcc
	s_mov_b32 s6, 0xf149f2ca
	s_waitcnt lgkmcnt(1)
	v_mfma_f32_16x16x32_bf16 v[8:11], v[8:11], v[0:3], 0
	s_waitcnt lgkmcnt(0)
	v_mfma_f32_16x16x32_bf16 v[8:11], v[136:139], v[4:7], v[8:11]
	s_nop 7
	v_mov_b32_e32 v20, v8
	v_pk_mul_f32 v[136:137], v[20:21], v[16:17]
	v_mov_b32_e32 v20, v9
	v_sub_f32_e32 v8, v136, v137
	v_cndmask_b32_e32 v12, v134, v8, vcc
	v_lshlrev_b32_e32 v8, s4, v32
	v_cvt_f32_u32_e32 v17, v8
	v_cmp_le_i32_e32 vcc, s26, v150
	s_and_b64 vcc, s[48:49], vcc
	v_pk_mul_f32 v[8:9], v[20:21], v[16:17]
	s_nop 0
	v_sub_f32_e32 v8, v8, v9
	v_cndmask_b32_e32 v136, v134, v8, vcc
	v_lshlrev_b32_e32 v8, s4, v33
	v_cvt_f32_u32_e32 v17, v8
	v_mov_b32_e32 v20, v10
	v_cmp_lt_i32_e32 vcc, s26, v151
	s_and_b64 vcc, s[50:51], vcc
	v_pk_mul_f32 v[8:9], v[20:21], v[16:17]
	v_mov_b32_e32 v20, v11
	v_sub_f32_e32 v8, v8, v9
	v_cndmask_b32_e32 v137, v134, v8, vcc
	v_lshlrev_b32_e32 v8, s4, v34
	v_cvt_f32_u32_e32 v17, v8
	v_cmp_lt_i32_e32 vcc, s26, v152
	s_and_b64 vcc, s[52:53], vcc
	v_max3_f32 v139, v12, s6, v136
	v_pk_mul_f32 v[8:9], v[20:21], v[16:17]
	v_lshlrev_b32_e32 v17, s4, v36
	v_sub_f32_e32 v8, v8, v9
	v_cndmask_b32_e32 v138, v134, v8, vcc
	ds_read_b128 v[8:11], v103
	ds_read_b128 v[140:143], v103 offset:64
	s_waitcnt lgkmcnt(1)
	v_mfma_f32_16x16x32_bf16 v[8:11], v[8:11], v[0:3], 0
	v_cvt_f32_u32_e32 v17, v17
	v_cmp_lt_i32_e32 vcc, s26, v35
	v_max3_f32 v139, v139, v137, v138
	s_waitcnt lgkmcnt(0)
	v_mfma_f32_16x16x32_bf16 v[8:11], v[140:143], v[4:7], v[8:11]
	s_nop 7
	v_mov_b32_e32 v20, v8
	v_pk_mul_f32 v[140:141], v[20:21], v[16:17]
	v_lshlrev_b32_e32 v17, s4, v38
	v_cvt_f32_u32_e32 v17, v17
	v_mov_b32_e32 v20, v9
	v_sub_f32_e32 v8, v140, v141
	v_cndmask_b32_e32 v8, v134, v8, vcc
	v_pk_mul_f32 v[140:141], v[20:21], v[16:17]
	v_lshlrev_b32_e32 v17, s4, v40
	v_cvt_f32_u32_e32 v17, v17
	v_mov_b32_e32 v20, v10
	v_cmp_lt_i32_e32 vcc, s26, v37
	v_sub_f32_e32 v9, v140, v141
	v_pk_mul_f32 v[140:141], v[20:21], v[16:17]
	v_cndmask_b32_e32 v9, v134, v9, vcc
	v_cmp_lt_i32_e32 vcc, s26, v39
	v_sub_f32_e32 v10, v140, v141
	v_max3_f32 v142, v139, v8, v9
	v_cndmask_b32_e32 v139, v134, v10, vcc
	v_lshlrev_b32_e32 v10, s4, v42
	v_cvt_f32_u32_e32 v17, v10
	v_mov_b32_e32 v20, v11
	v_cmp_lt_i32_e32 vcc, s26, v41
	v_pk_mul_f32 v[10:11], v[20:21], v[16:17]
	s_nop 0
	v_sub_f32_e32 v10, v10, v11
	v_cndmask_b32_e32 v10, v134, v10, vcc
	v_max3_f32 v148, v142, v139, v10
	ds_read_b128 v[140:143], v104
	ds_read_b128 v[144:147], v104 offset:64
	s_waitcnt lgkmcnt(1)
	v_mfma_f32_16x16x32_bf16 v[140:143], v[140:143], v[0:3], 0
	v_lshlrev_b32_e32 v11, s4, v44
	v_cvt_f32_u32_e32 v17, v11
	v_cmp_lt_i32_e32 vcc, s26, v43
	s_waitcnt lgkmcnt(0)
	v_mfma_f32_16x16x32_bf16 v[140:143], v[144:147], v[4:7], v[140:143]
	s_nop 7
	v_mov_b32_e32 v20, v140
	v_pk_mul_f32 v[144:145], v[20:21], v[16:17]
	v_lshlrev_b32_e32 v17, s4, v46
	v_cvt_f32_u32_e32 v17, v17
	v_mov_b32_e32 v20, v141
	v_sub_f32_e32 v11, v144, v145
	v_cndmask_b32_e32 v11, v134, v11, vcc
	v_pk_mul_f32 v[140:141], v[20:21], v[16:17]
	v_cmp_lt_i32_e32 vcc, s26, v45
	v_sub_f32_e32 v17, v140, v141
	v_mov_b32_e32 v20, v142
	v_cndmask_b32_e32 v140, v134, v17, vcc
	v_lshlrev_b32_e32 v17, s4, v48
	v_cvt_f32_u32_e32 v17, v17
	v_cmp_lt_i32_e32 vcc, s26, v47
	v_max3_f32 v146, v148, v11, v140
	v_pk_mul_f32 v[144:145], v[20:21], v[16:17]
	s_nop 0
	v_sub_f32_e32 v17, v144, v145
	v_cndmask_b32_e32 v142, v134, v17, vcc
	v_lshlrev_b32_e32 v17, s4, v50
	v_cvt_f32_u32_e32 v17, v17
	v_mov_b32_e32 v20, v143
	v_cmp_lt_i32_e32 vcc, s26, v49
	v_pk_mul_f32 v[144:145], v[20:21], v[16:17]
	s_nop 0
	v_sub_f32_e32 v17, v144, v145
	v_cndmask_b32_e32 v141, v134, v17, vcc
	v_max3_f32 v155, v146, v142, v141
	ds_read_b128 v[144:147], v105
	ds_read_b128 v[156:159], v105 offset:64
	s_waitcnt lgkmcnt(1)
	v_mfma_f32_16x16x32_bf16 v[144:147], v[144:147], v[0:3], 0
	v_lshlrev_b32_e32 v17, s4, v52
	v_cvt_f32_u32_e32 v17, v17
	v_cmp_lt_i32_e32 vcc, s26, v51
	s_waitcnt lgkmcnt(0)
	v_mfma_f32_16x16x32_bf16 v[144:147], v[156:159], v[4:7], v[144:147]
	ds_read_b128 v[156:159], v106
	ds_read_b128 v[166:169], v106 offset:64
	s_waitcnt lgkmcnt(1)
	v_mfma_f32_16x16x32_bf16 v[156:159], v[156:159], v[0:3], 0
	s_nop 3
	v_mov_b32_e32 v20, v144
	v_pk_mul_f32 v[148:149], v[20:21], v[16:17]
	v_mov_b32_e32 v20, v145
	v_sub_f32_e32 v17, v148, v149
	v_cndmask_b32_e32 v143, v134, v17, vcc
	v_lshlrev_b32_e32 v17, s4, v54
	v_cvt_f32_u32_e32 v17, v17
	v_cmp_lt_i32_e32 vcc, s26, v53
	s_waitcnt lgkmcnt(0)
; #define LAS __attribute__((address_space(3)))
; __device__ __forceinline__ void attn_prompt_item(LAS unsigned char* lds, const bf16_t* qkvb, bf16_t* og, float* lse, int it, int tid, int wave, int lane) {
;     ...
; #pragma unroll
;     for (int T = 0; T < 9; ++T) {
;         const LAS bf16_t* kr = Kl + (16 * (wave + T) + ql) * KL_PITCH + 8 * fq;
;         const bf16x8 a0 = *(const LAS bf16x8*)kr, a1 = *(const LAS bf16x8*)(kr + 32);
;         f32x4 acc = (f32x4){0.f, 0.f, 0.f, 0.f};
;         acc = __builtin_amdgcn_mfma_f32_16x16x32_bf16(a0, q0, acc, 0, 0, 0);
;         acc = __builtin_amdgcn_mfma_f32_16x16x32_bf16(a1, q1, acc, 0, 0, 0);
; #pragma unroll
;         for (int j = 0; j < 4; ++j) {
;             const int krel = 16 * T + 4 * fq + j, delta = 128 + ql - krel, ksub = qb * 128 - 128 + 16 * wave + krel;
;             const bool valid = (delta >= 0) && (delta <= 128) && (ksub >= 0);
;             const float s = valid ? acc[j] * 0.125f - slope * (float)(delta * dil) : -1e30f;
;             acc[j] = s; mx = fmaxf(mx, s); }
;         sc[T] = acc;
;     }
	v_mfma_f32_16x16x32_bf16 v[156:159], v[166:169], v[4:7], v[156:159]
	v_mul_f32_e64 v144, v20, v16
	v_mul_f32_e64 v145, v21, v17
	v_sub_f32_e32 v17, v144, v145
	v_cndmask_b32_e32 v144, v134, v17, vcc
	v_lshlrev_b32_e32 v17, s4, v56
	v_cvt_f32_u32_e32 v17, v17
	v_mov_b32_e32 v20, v146
	v_cmp_lt_i32_e32 vcc, s26, v55
	v_max3_f32 v155, v155, v143, v144
	v_pk_mul_f32 v[148:149], v[20:21], v[16:17]
	v_mov_b32_e32 v20, v147
	v_sub_f32_e32 v17, v148, v149
	v_cndmask_b32_e32 v146, v134, v17, vcc
	v_lshlrev_b32_e32 v17, s4, v58
	v_cvt_f32_u32_e32 v17, v17
	v_cmp_lt_i32_e32 vcc, s26, v57
	v_pk_mul_f32 v[148:149], v[20:21], v[16:17]
	s_nop 0
	v_sub_f32_e32 v17, v148, v149
	v_cndmask_b32_e32 v145, v134, v17, vcc
	v_lshlrev_b32_e32 v17, s4, v60
	v_cvt_f32_u32_e32 v17, v17
	v_mov_b32_e32 v20, v156
	v_cmp_lt_i32_e32 vcc, s26, v59
	v_max3_f32 v155, v155, v146, v145
	v_pk_mul_f32 v[148:149], v[20:21], v[16:17]
	v_mov_b32_e32 v20, v157
	v_sub_f32_e32 v17, v148, v149
	v_cndmask_b32_e32 v147, v134, v17, vcc
	v_lshlrev_b32_e32 v17, s4, v62
	v_cvt_f32_u32_e32 v17, v17
	v_cmp_lt_i32_e32 vcc, s26, v61
	v_pk_mul_f32 v[148:149], v[20:21], v[16:17]
	s_nop 0
	v_sub_f32_e32 v17, v148, v149
	v_cndmask_b32_e32 v148, v134, v17, vcc
	v_lshlrev_b32_e32 v17, s4, v64
	v_cvt_f32_u32_e32 v17, v17
	v_mov_b32_e32 v20, v158
	v_cmp_lt_i32_e32 vcc, s26, v63
	v_max3_f32 v163, v155, v147, v148
	v_pk_mul_f32 v[156:157], v[20:21], v[16:17]
	v_mov_b32_e32 v20, v159
	v_sub_f32_e32 v17, v156, v157
	v_cndmask_b32_e32 v155, v134, v17, vcc
	v_lshlrev_b32_e32 v17, s4, v66
	v_cvt_f32_u32_e32 v17, v17
	v_cmp_lt_i32_e32 vcc, s26, v65
	v_pk_mul_f32 v[156:157], v[20:21], v[16:17]
	s_nop 0
	v_sub_f32_e32 v17, v156, v157
	ds_read_b128 v[156:159], v107
	ds_read_b128 v[166:169], v107 offset:64
	s_waitcnt lgkmcnt(1)
	v_mfma_f32_16x16x32_bf16 v[156:159], v[156:159], v[0:3], 0
	v_cndmask_b32_e32 v149, v134, v17, vcc
	v_lshlrev_b32_e32 v17, s4, v68
	v_cvt_f32_u32_e32 v17, v17
	s_waitcnt lgkmcnt(0)
	v_mfma_f32_16x16x32_bf16 v[166:169], v[166:169], v[4:7], v[156:159]
	v_cmp_lt_i32_e32 vcc, s26, v67
	v_max3_f32 v163, v163, v155, v149
	s_nop 5
	v_mov_b32_e32 v20, v166
	v_pk_mul_f32 v[156:157], v[20:21], v[16:17]
	v_mov_b32_e32 v20, v167
	v_sub_f32_e32 v17, v156, v157
	v_cndmask_b32_e32 v156, v134, v17, vcc
	v_lshlrev_b32_e32 v17, s4, v70
	v_cvt_f32_u32_e32 v17, v17
	v_cmp_lt_i32_e32 vcc, s26, v69
	v_pk_mul_f32 v[158:159], v[20:21], v[16:17]
	s_nop 0
	v_sub_f32_e32 v17, v158, v159
	v_cndmask_b32_e32 v157, v134, v17, vcc
	v_lshlrev_b32_e32 v17, s4, v72
	v_cvt_f32_u32_e32 v17, v17
	v_mov_b32_e32 v20, v168
	v_cmp_lt_i32_e32 vcc, s26, v71
	v_max3_f32 v163, v163, v156, v157
	v_pk_mul_f32 v[158:159], v[20:21], v[16:17]
	v_mov_b32_e32 v20, v169
	v_sub_f32_e32 v17, v158, v159
	v_cndmask_b32_e32 v159, v134, v17, vcc
	v_lshlrev_b32_e32 v17, s4, v74
	v_cvt_f32_u32_e32 v17, v17
	v_cmp_lt_i32_e32 vcc, s26, v73
	v_pk_mul_f32 v[166:167], v[20:21], v[16:17]
	s_nop 0
	v_sub_f32_e32 v17, v166, v167
	ds_read_b128 v[166:169], v108
	ds_read_b128 v[178:181], v108 offset:64
	s_waitcnt lgkmcnt(1)
	v_mfma_f32_16x16x32_bf16 v[166:169], v[166:169], v[0:3], 0
	v_cndmask_b32_e32 v158, v134, v17, vcc
	v_lshlrev_b32_e32 v17, s4, v76
	v_cvt_f32_u32_e32 v17, v17
	s_waitcnt lgkmcnt(0)
	v_mfma_f32_16x16x32_bf16 v[166:169], v[178:181], v[4:7], v[166:169]
	v_cmp_lt_i32_e32 vcc, s26, v75
	v_max3_f32 v171, v163, v159, v158
	ds_read_b128 v[178:181], v109
	ds_read_b128 v[182:185], v109 offset:64
	s_waitcnt lgkmcnt(1)
	v_mfma_f32_16x16x32_bf16 v[178:181], v[178:181], v[0:3], 0
	s_nop 1
	v_mov_b32_e32 v20, v166
	v_pk_mul_f32 v[172:173], v[20:21], v[16:17]
	v_mov_b32_e32 v20, v167
	v_sub_f32_e32 v17, v172, v173
	v_cndmask_b32_e32 v163, v134, v17, vcc
	v_lshlrev_b32_e32 v17, s4, v78
	v_cvt_f32_u32_e32 v17, v17
	v_cmp_lt_i32_e32 vcc, s26, v77
	s_waitcnt lgkmcnt(0)
	v_mfma_f32_16x16x32_bf16 v[178:181], v[182:185], v[4:7], v[178:181]
	v_mul_f32_e64 v166, v20, v16
	v_mul_f32_e64 v167, v21, v17
	v_sub_f32_e32 v17, v166, v167
	v_cndmask_b32_e32 v166, v134, v17, vcc
	v_lshlrev_b32_e32 v17, s4, v80
	v_cvt_f32_u32_e32 v17, v17
	v_mov_b32_e32 v20, v168
	v_cmp_lt_i32_e32 vcc, s26, v79
	v_max3_f32 v171, v171, v163, v166
	v_pk_mul_f32 v[172:173], v[20:21], v[16:17]
	v_mov_b32_e32 v20, v169
	v_sub_f32_e32 v17, v172, v173
	v_cndmask_b32_e32 v168, v134, v17, vcc
	v_lshlrev_b32_e32 v17, s4, v82
	v_cvt_f32_u32_e32 v17, v17
	v_cmp_lt_i32_e32 vcc, s26, v81
	v_pk_mul_f32 v[172:173], v[20:21], v[16:17]
	s_nop 0
	v_sub_f32_e32 v17, v172, v173
	v_cndmask_b32_e32 v167, v134, v17, vcc
	v_lshlrev_b32_e32 v17, s4, v84
	v_cvt_f32_u32_e32 v17, v17
	v_mov_b32_e32 v20, v178
	v_cmp_lt_i32_e32 vcc, s26, v83
	v_max3_f32 v186, v171, v168, v167
	v_pk_mul_f32 v[172:173], v[20:21], v[16:17]
	v_mov_b32_e32 v20, v179
	v_sub_f32_e32 v17, v172, v173
	v_cndmask_b32_e32 v169, v134, v17, vcc
	v_lshlrev_b32_e32 v17, s4, v86
	v_cvt_f32_u32_e32 v17, v17
	v_cmp_lt_i32_e32 vcc, s26, v85
	v_pk_mul_f32 v[172:173], v[20:21], v[16:17]
	s_nop 0
	v_sub_f32_e32 v17, v172, v173
	v_cndmask_b32_e32 v171, v134, v17, vcc
	v_lshlrev_b32_e32 v17, s4, v88
	v_cvt_f32_u32_e32 v17, v17
	v_mov_b32_e32 v20, v180
	v_cmp_lt_i32_e32 vcc, s26, v87
	v_max3_f32 v182, v186, v169, v171
	v_pk_mul_f32 v[172:173], v[20:21], v[16:17]
	v_mov_b32_e32 v20, v181
	v_sub_f32_e32 v17, v172, v173
	v_cndmask_b32_e32 v173, v134, v17, vcc
	v_lshlrev_b32_e32 v17, s4, v90
	v_cvt_f32_u32_e32 v17, v17
	v_cmp_lt_i32_e32 vcc, s26, v89
	v_pk_mul_f32 v[178:179], v[20:21], v[16:17]
	s_nop 0
	v_sub_f32_e32 v17, v178, v179
	v_cndmask_b32_e32 v172, v134, v17, vcc
	v_max3_f32 v186, v182, v173, v172
	ds_read_b128 v[178:181], v110
	ds_read_b128 v[182:185], v110 offset:64
	s_waitcnt lgkmcnt(1)
; __device__ __forceinline__ unsigned cvt_pk_bf16(float lo, float hi) { unsigned r; asm volatile("v_cvt_pk_bf16_f32 %0, %1, %2" : "=v"(r) : "v"(lo), "v"(hi)); return r; }
; #define LAS __attribute__((address_space(3)))
; __device__ __forceinline__ void attn_prompt_item(LAS unsigned char* lds, const bf16_t* qkvb, bf16_t* og, float* lse, int it, int tid, int wave, int lane) {
;     ...
; #pragma unroll
;     for (int T = 0; T < 9; ++T) {
;         const LAS bf16_t* kr = Kl + (16 * (wave + T) + ql) * KL_PITCH + 8 * fq;
;         const bf16x8 a0 = *(const LAS bf16x8*)kr, a1 = *(const LAS bf16x8*)(kr + 32);
;         f32x4 acc = (f32x4){0.f, 0.f, 0.f, 0.f};
;         acc = __builtin_amdgcn_mfma_f32_16x16x32_bf16(a0, q0, acc, 0, 0, 0);
;         acc = __builtin_amdgcn_mfma_f32_16x16x32_bf16(a1, q1, acc, 0, 0, 0);
; #pragma unroll
;         for (int j = 0; j < 4; ++j) {
;             const int krel = 16 * T + 4 * fq + j, delta = 128 + ql - krel, ksub = qb * 128 - 128 + 16 * wave + krel;
;             const bool valid = (delta >= 0) && (delta <= 128) && (ksub >= 0);
;             const float s = valid ? acc[j] * 0.125f - slope * (float)(delta * dil) : -1e30f;
;             acc[j] = s; mx = fmaxf(mx, s); }
;         sc[T] = acc;
;     }
;     mx = fmaxf(mx, __shfl_xor(mx, 16)); mx = fmaxf(mx, __shfl_xor(mx, 32));
;     float den = 0.f;
; #pragma unroll
;     for (int T = 0; T < 9; ++T) {
;         f32x4 p;
; #pragma unroll
;         for (int j = 0; j < 4; ++j) { p[j] = sc[T][j] > -1e29f ? __expf(sc[T][j] - mx) : 0.f; den += p[j]; }
;         u32x2 w; w.x = cvt_pk_bf16(p[0], p[1]); w.y = cvt_pk_bf16(p[2], p[3]);
;         *(LAS u32x2*)(Pw + ql * PW_PITCH + 16 * T + 4 * fq) = w;
;     }
	v_mfma_f32_16x16x32_bf16 v[0:3], v[178:181], v[0:3], 0
	v_cmp_lt_f32_e32 vcc, s67, v12
	s_waitcnt lgkmcnt(0)
	v_mfma_f32_16x16x32_bf16 v[2:5], v[182:185], v[4:7], v[0:3]
	s_nop 4
	v_lshlrev_b32_e32 v0, s4, v91
	v_cvt_f32_i32_e32 v17, v0
	s_nop 0
	v_mov_b32_e32 v20, v2
	v_pk_mul_f32 v[0:1], v[20:21], v[16:17]
	s_nop 0
	v_sub_f32_e32 v0, v0, v1
	v_lshlrev_b32_e32 v1, s4, v92
	v_cvt_f32_i32_e32 v17, v1
	v_mov_b32_e32 v20, v3
	v_cndmask_b32_e64 v0, v134, v0, s[54:55]
	v_pk_mul_f32 v[2:3], v[20:21], v[16:17]
	s_nop 0
	v_sub_f32_e32 v1, v2, v3
	v_lshlrev_b32_e32 v2, s4, v93
	v_cvt_f32_i32_e32 v17, v2
	v_mov_b32_e32 v20, v4
	v_cndmask_b32_e64 v1, v134, v1, s[56:57]
	v_max3_f32 v6, v186, v0, v1
	v_pk_mul_f32 v[2:3], v[20:21], v[16:17]
	v_mov_b32_e32 v20, v5
	v_sub_f32_e32 v2, v2, v3
	v_cndmask_b32_e64 v3, v134, v2, s[58:59]
	v_lshlrev_b32_e32 v2, s4, v94
	v_cvt_f32_i32_e32 v17, v2
	v_pk_mul_f32 v[4:5], v[20:21], v[16:17]
	s_nop 0
	v_sub_f32_e32 v2, v4, v5
	v_cndmask_b32_e64 v4, v134, v2, s[60:61]
	v_max3_f32 v2, v6, v3, v4
	ds_bpermute_b32 v5, v96, v2
	s_waitcnt lgkmcnt(0)
	v_max_f32_e32 v5, v5, v5
	v_max_f32_e32 v2, v2, v5
	ds_bpermute_b32 v5, v97, v2
	s_waitcnt lgkmcnt(0)
	v_max_f32_e32 v5, v5, v5
	v_max_f32_e32 v2, v2, v5
	v_sub_f32_e32 v5, v12, v2
	v_mul_f32_e32 v5, 0x3fb8aa3b, v5
	v_sub_f32_e32 v7, v136, v2
	v_exp_f32_e32 v5, v5
	v_mul_f32_e32 v7, 0x3fb8aa3b, v7
	v_sub_f32_e32 v12, v137, v2
	v_exp_f32_e32 v7, v7
	v_mul_f32_e32 v12, 0x3fb8aa3b, v12
	v_sub_f32_e32 v17, v138, v2
	v_exp_f32_e32 v12, v12
	v_mul_f32_e32 v17, 0x3fb8aa3b, v17
	v_exp_f32_e32 v17, v17
	v_cndmask_b32_e32 v5, 0, v5, vcc
	v_cmp_lt_f32_e32 vcc, s67, v136
	v_add_f32_e32 v6, 0, v5
	s_nop 0
	v_cndmask_b32_e32 v7, 0, v7, vcc
	v_cmp_lt_f32_e32 vcc, s67, v137
	v_add_f32_e32 v6, v7, v6
	s_nop 0
	v_cndmask_b32_e32 v12, 0, v12, vcc
	v_cmp_lt_f32_e32 vcc, s67, v138
	v_add_f32_e32 v6, v12, v6
	s_nop 0
	v_cndmask_b32_e32 v17, 0, v17, vcc
	v_add_f32_e32 v20, v17, v6
	v_cvt_pk_bf16_f32 v6, v5, v7
	v_sub_f32_e32 v5, v8, v2
	v_mul_f32_e32 v5, 0x3fb8aa3b, v5
	v_exp_f32_e32 v5, v5
	v_cvt_pk_bf16_f32 v7, v12, v17
	ds_write_b64 v95, v[6:7]
	v_sub_f32_e32 v7, v9, v2
	v_cmp_lt_f32_e32 vcc, s67, v8
	v_mul_f32_e32 v7, 0x3fb8aa3b, v7
	v_sub_f32_e32 v8, v139, v2
	v_cndmask_b32_e32 v5, 0, v5, vcc
	v_cmp_lt_f32_e32 vcc, s67, v9
	v_exp_f32_e32 v7, v7
	v_mul_f32_e32 v8, 0x3fb8aa3b, v8
	v_sub_f32_e32 v9, v10, v2
	v_exp_f32_e32 v8, v8
	v_mul_f32_e32 v9, 0x3fb8aa3b, v9
	v_exp_f32_e32 v9, v9
	v_add_f32_e32 v6, v5, v20
	v_cndmask_b32_e32 v7, 0, v7, vcc
	v_cmp_lt_f32_e32 vcc, s67, v139
	v_add_f32_e32 v6, v7, v6
	v_mov_b32_e32 v12, v13
	v_cndmask_b32_e32 v8, 0, v8, vcc
	v_cmp_lt_f32_e32 vcc, s67, v10
	v_add_f32_e32 v6, v8, v6
	s_nop 0
	v_cndmask_b32_e32 v9, 0, v9, vcc
	v_add_f32_e32 v10, v9, v6
	v_cvt_pk_bf16_f32 v6, v5, v7
	v_cvt_pk_bf16_f32 v7, v8, v9
	v_sub_f32_e32 v5, v11, v2
	ds_write_b64 v95, v[6:7] offset:32
	v_mul_f32_e32 v5, 0x3fb8aa3b, v5
	v_sub_f32_e32 v7, v140, v2
	v_exp_f32_e32 v5, v5
	v_mul_f32_e32 v7, 0x3fb8aa3b, v7
	v_sub_f32_e32 v8, v142, v2
	v_exp_f32_e32 v7, v7
	v_mul_f32_e32 v8, 0x3fb8aa3b, v8
	v_sub_f32_e32 v9, v141, v2
	v_exp_f32_e32 v8, v8
	v_mul_f32_e32 v9, 0x3fb8aa3b, v9
	v_cmp_lt_f32_e32 vcc, s67, v11
	v_exp_f32_e32 v9, v9
	s_nop 0
	v_cndmask_b32_e32 v5, 0, v5, vcc
	v_cmp_lt_f32_e32 vcc, s67, v140
	v_add_f32_e32 v6, v5, v10
	s_nop 0
	v_cndmask_b32_e32 v7, 0, v7, vcc
	v_cmp_lt_f32_e32 vcc, s67, v142
	v_add_f32_e32 v6, v7, v6
	s_nop 0
	v_cndmask_b32_e32 v8, 0, v8, vcc
	v_cmp_lt_f32_e32 vcc, s67, v141
	v_add_f32_e32 v6, v8, v6
	s_nop 0
	v_cndmask_b32_e32 v9, 0, v9, vcc
	v_add_f32_e32 v10, v9, v6
	v_cvt_pk_bf16_f32 v6, v5, v7
	v_cvt_pk_bf16_f32 v7, v8, v9
	v_sub_f32_e32 v5, v143, v2
	ds_write_b64 v95, v[6:7] offset:64
	v_mul_f32_e32 v5, 0x3fb8aa3b, v5
	v_sub_f32_e32 v7, v144, v2
	v_exp_f32_e32 v5, v5
	v_mul_f32_e32 v7, 0x3fb8aa3b, v7
	v_sub_f32_e32 v8, v146, v2
	v_exp_f32_e32 v7, v7
	v_mul_f32_e32 v8, 0x3fb8aa3b, v8
	v_sub_f32_e32 v9, v145, v2
	v_exp_f32_e32 v8, v8
	v_mul_f32_e32 v9, 0x3fb8aa3b, v9
	v_cmp_lt_f32_e32 vcc, s67, v143
	v_exp_f32_e32 v9, v9
	s_nop 0
	v_cndmask_b32_e32 v5, 0, v5, vcc
	v_cmp_lt_f32_e32 vcc, s67, v144
	v_add_f32_e32 v6, v5, v10
	s_nop 0
	v_cndmask_b32_e32 v7, 0, v7, vcc
	v_cmp_lt_f32_e32 vcc, s67, v146
	v_add_f32_e32 v6, v7, v6
	s_nop 0
	v_cndmask_b32_e32 v8, 0, v8, vcc
	v_cmp_lt_f32_e32 vcc, s67, v145
	v_add_f32_e32 v6, v8, v6
	s_nop 0
	v_cndmask_b32_e32 v9, 0, v9, vcc
	v_add_f32_e32 v10, v9, v6
	v_cvt_pk_bf16_f32 v6, v5, v7
	v_cvt_pk_bf16_f32 v7, v8, v9
	v_sub_f32_e32 v5, v147, v2
	ds_write_b64 v95, v[6:7] offset:96
	v_mul_f32_e32 v5, 0x3fb8aa3b, v5
	v_sub_f32_e32 v7, v148, v2
	v_exp_f32_e32 v5, v5
	v_mul_f32_e32 v7, 0x3fb8aa3b, v7
	v_sub_f32_e32 v8, v155, v2
	v_exp_f32_e32 v7, v7
	v_mul_f32_e32 v8, 0x3fb8aa3b, v8
	v_sub_f32_e32 v9, v149, v2
	v_exp_f32_e32 v8, v8
	v_mul_f32_e32 v9, 0x3fb8aa3b, v9
	v_cmp_lt_f32_e32 vcc, s67, v147
	v_exp_f32_e32 v9, v9
	s_nop 0
	v_cndmask_b32_e32 v5, 0, v5, vcc
	v_cmp_lt_f32_e32 vcc, s67, v148
	v_add_f32_e32 v6, v5, v10
	s_nop 0
	v_cndmask_b32_e32 v7, 0, v7, vcc
	v_cmp_lt_f32_e32 vcc, s67, v155
	v_add_f32_e32 v6, v7, v6
	s_nop 0
	v_cndmask_b32_e32 v8, 0, v8, vcc
	v_cmp_lt_f32_e32 vcc, s67, v149
	v_add_f32_e32 v6, v8, v6
	s_nop 0
	v_cndmask_b32_e32 v9, 0, v9, vcc
	v_add_f32_e32 v10, v9, v6
	v_cvt_pk_bf16_f32 v6, v5, v7
	v_cvt_pk_bf16_f32 v7, v8, v9
	v_sub_f32_e32 v5, v156, v2
	ds_write_b64 v95, v[6:7] offset:128
	v_mul_f32_e32 v5, 0x3fb8aa3b, v5
	v_sub_f32_e32 v7, v157, v2
	v_exp_f32_e32 v5, v5
	v_mul_f32_e32 v7, 0x3fb8aa3b, v7
	v_sub_f32_e32 v8, v159, v2
	v_exp_f32_e32 v7, v7
	v_mul_f32_e32 v8, 0x3fb8aa3b, v8
; __device__ __forceinline__ unsigned cvt_pk_bf16(float lo, float hi) { unsigned r; asm volatile("v_cvt_pk_bf16_f32 %0, %1, %2" : "=v"(r) : "v"(lo), "v"(hi)); return r; }
; #define LAS __attribute__((address_space(3)))
; __device__ __forceinline__ void attn_prompt_item(LAS unsigned char* lds, const bf16_t* qkvb, bf16_t* og, float* lse, int it, int tid, int wave, int lane) {
;     ...
; #pragma unroll
;     for (int T = 0; T < 9; ++T) {
;         f32x4 p;
; #pragma unroll
;         for (int j = 0; j < 4; ++j) { p[j] = sc[T][j] > -1e29f ? __expf(sc[T][j] - mx) : 0.f; den += p[j]; }
;         u32x2 w; w.x = cvt_pk_bf16(p[0], p[1]); w.y = cvt_pk_bf16(p[2], p[3]);
;         *(LAS u32x2*)(Pw + ql * PW_PITCH + 16 * T + 4 * fq) = w;
;     }
	v_sub_f32_e32 v9, v158, v2
	v_exp_f32_e32 v8, v8
	v_mul_f32_e32 v9, 0x3fb8aa3b, v9
	v_cmp_lt_f32_e32 vcc, s67, v156
	v_exp_f32_e32 v9, v9
	s_nop 0
	v_cndmask_b32_e32 v5, 0, v5, vcc
	v_cmp_lt_f32_e32 vcc, s67, v157
	v_add_f32_e32 v6, v5, v10
	s_nop 0
	v_cndmask_b32_e32 v7, 0, v7, vcc
	v_cmp_lt_f32_e32 vcc, s67, v159
	v_add_f32_e32 v6, v7, v6
	s_nop 0
	v_cndmask_b32_e32 v8, 0, v8, vcc
	v_cmp_lt_f32_e32 vcc, s67, v158
	v_add_f32_e32 v6, v8, v6
	s_nop 0
	v_cndmask_b32_e32 v9, 0, v9, vcc
	v_add_f32_e32 v10, v9, v6
	v_cvt_pk_bf16_f32 v6, v5, v7
	v_cvt_pk_bf16_f32 v7, v8, v9
	v_sub_f32_e32 v5, v163, v2
	ds_write_b64 v95, v[6:7] offset:160
	v_mul_f32_e32 v5, 0x3fb8aa3b, v5
	v_sub_f32_e32 v7, v166, v2
	v_exp_f32_e32 v5, v5
	v_mul_f32_e32 v7, 0x3fb8aa3b, v7
	v_sub_f32_e32 v8, v168, v2
	v_exp_f32_e32 v7, v7
	v_mul_f32_e32 v8, 0x3fb8aa3b, v8
	v_sub_f32_e32 v9, v167, v2
	v_exp_f32_e32 v8, v8
	v_mul_f32_e32 v9, 0x3fb8aa3b, v9
	v_cmp_lt_f32_e32 vcc, s67, v163
	v_exp_f32_e32 v9, v9
	s_nop 0
	v_cndmask_b32_e32 v5, 0, v5, vcc
	v_cmp_lt_f32_e32 vcc, s67, v166
	v_add_f32_e32 v6, v5, v10
	s_nop 0
	v_cndmask_b32_e32 v7, 0, v7, vcc
	v_cmp_lt_f32_e32 vcc, s67, v168
	v_add_f32_e32 v6, v7, v6
	s_nop 0
	v_cndmask_b32_e32 v8, 0, v8, vcc
	v_cmp_lt_f32_e32 vcc, s67, v167
	v_add_f32_e32 v6, v8, v6
	s_nop 0
	v_cndmask_b32_e32 v9, 0, v9, vcc
	v_add_f32_e32 v10, v9, v6
	v_cvt_pk_bf16_f32 v6, v5, v7
	v_cvt_pk_bf16_f32 v7, v8, v9
	v_sub_f32_e32 v5, v169, v2
	ds_write_b64 v95, v[6:7] offset:192
	v_mul_f32_e32 v5, 0x3fb8aa3b, v5
	v_sub_f32_e32 v7, v171, v2
	v_exp_f32_e32 v5, v5
	v_mul_f32_e32 v7, 0x3fb8aa3b, v7
	v_sub_f32_e32 v8, v173, v2
	v_exp_f32_e32 v7, v7
	v_mul_f32_e32 v8, 0x3fb8aa3b, v8
	v_sub_f32_e32 v9, v172, v2
	v_exp_f32_e32 v8, v8
	v_mul_f32_e32 v9, 0x3fb8aa3b, v9
	v_cmp_lt_f32_e32 vcc, s67, v169
	v_exp_f32_e32 v9, v9
	s_nop 0
	v_cndmask_b32_e32 v5, 0, v5, vcc
	v_cmp_lt_f32_e32 vcc, s67, v171
	v_add_f32_e32 v6, v5, v10
	s_nop 0
	v_cndmask_b32_e32 v7, 0, v7, vcc
	v_cmp_lt_f32_e32 vcc, s67, v173
	v_add_f32_e32 v6, v7, v6
	s_nop 0
	v_cndmask_b32_e32 v8, 0, v8, vcc
	v_cmp_lt_f32_e32 vcc, s67, v172
	v_add_f32_e32 v6, v8, v6
	s_nop 0
	v_cndmask_b32_e32 v9, 0, v9, vcc
	v_cmp_lt_f32_e32 vcc, s67, v0
	v_sub_f32_e32 v0, v0, v2
	v_mul_f32_e32 v0, 0x3fb8aa3b, v0
	v_exp_f32_e32 v0, v0
	v_add_f32_e32 v10, v9, v6
	v_cvt_pk_bf16_f32 v6, v5, v7
	v_cvt_pk_bf16_f32 v7, v8, v9
	v_cndmask_b32_e32 v0, 0, v0, vcc
	v_cmp_lt_f32_e32 vcc, s67, v1
	v_sub_f32_e32 v1, v1, v2
	v_mul_f32_e32 v1, 0x3fb8aa3b, v1
	v_exp_f32_e32 v1, v1
	v_add_f32_e32 v5, v0, v10
	ds_write_b64 v95, v[6:7] offset:224
	v_cndmask_b32_e32 v1, 0, v1, vcc
	v_cmp_lt_f32_e32 vcc, s67, v3
	v_sub_f32_e32 v3, v3, v2
	v_mul_f32_e32 v3, 0x3fb8aa3b, v3
	v_exp_f32_e32 v3, v3
	v_add_f32_e32 v5, v1, v5
	v_cvt_pk_bf16_f32 v0, v0, v1
	v_cndmask_b32_e32 v3, 0, v3, vcc
	v_cmp_lt_f32_e32 vcc, s67, v4
	v_sub_f32_e32 v4, v4, v2
	v_mul_f32_e32 v4, 0x3fb8aa3b, v4
	v_exp_f32_e32 v4, v4
	v_add_f32_e32 v5, v3, v5
	v_cndmask_b32_e32 v4, 0, v4, vcc
	v_add_f32_e32 v5, v4, v5
	v_cvt_pk_bf16_f32 v1, v3, v4
	ds_write2_b64 v95, v[0:1], v[12:13] offset0:32 offset1:36
	ds_bpermute_b32 v0, v96, v5
	s_waitcnt lgkmcnt(0)
	s_barrier
; __device__ __forceinline__ unsigned cvt_pk_bf16(float lo, float hi) { unsigned r; asm volatile("v_cvt_pk_bf16_f32 %0, %1, %2" : "=v"(r) : "v"(lo), "v"(hi)); return r; }
; #define LAS __attribute__((address_space(3)))
; __device__ __forceinline__ void attn_prompt_item(LAS unsigned char* lds, const bf16_t* qkvb, bf16_t* og, float* lse, int it, int tid, int wave, int lane) {
;     ...
;     den += __shfl_xor(den, 16); den += __shfl_xor(den, 32);
;     const float inv = 1.0f / den;
;     __syncthreads();
;     bf16_t* op = og + qrow * AW + g * 256 + hh * 64 + 4 * fq;
; #pragma unroll
;     for (int dt = 0; dt < 4; ++dt) {
;         f32x4 o = (f32x4){0.f, 0.f, 0.f, 0.f};
; #pragma unroll
;         for (int ks = 0; ks < 5; ++ks) {
;             const bf16x8 av = *(const LAS bf16x8*)(Vt + (16 * dt + ql) * VT_PITCH + (((2 * wave + 4 * ks + fq) ^ ((2 * dt + (ql >> 3)) & 7)) << 3));
;             const bf16x8 bp = *(const LAS bf16x8*)(Pw + ql * PW_PITCH + 32 * ks + 8 * fq);
;             o = __builtin_amdgcn_mfma_f32_16x16x32_bf16(av, bp, o, 0, 0, 0); }
;         u32x2 w; w.x = cvt_pk_bf16(o[0] * inv, o[1] * inv); w.y = cvt_pk_bf16(o[2] * inv, o[3] * inv);
;         *(u32x2*)(op + 16 * dt) = w;
;     }
;     if (fq == 0) lse[qrow * 12 + g * 4 + hh] = mx + __logf(den);
	v_lshlrev_b32_e32 v12, 1, v150
	v_add_f32_e32 v0, v5, v0
	ds_bpermute_b32 v1, v97, v0
	s_waitcnt lgkmcnt(0)
	v_add_f32_e32 v3, v0, v1
	v_div_scale_f32 v0, s[6:7], v3, v3, 1.0
	v_rcp_f32_e32 v1, v0
	s_nop 0
	v_fma_f32 v4, -v0, v1, 1.0
	v_fmac_f32_e32 v1, v4, v1
	v_div_scale_f32 v4, vcc, 1.0, v3, 1.0
	v_mul_f32_e32 v5, v4, v1
	v_fma_f32 v6, -v0, v5, v4
	v_fmac_f32_e32 v5, v6, v1
	v_fma_f32 v0, -v0, v5, v4
	v_div_fmas_f32 v0, v0, v1, v5
	v_div_fixup_f32 v17, v0, v3, 1.0
	v_mov_b64_e32 v[0:1], s[34:35]
	v_mad_u64_u32 v[0:1], s[6:7], v18, s27, v[0:1]
	v_mov_b32_e32 v4, v1
	v_mad_u64_u32 v[4:5], s[6:7], v19, s27, v[4:5]
	v_mov_b32_e32 v1, v4
	ds_read_b128 v[4:7], v111 offset:36864
	v_lshl_add_u64 v[0:1], v[0:1], 0, s[80:81]
	v_lshl_add_u64 v[0:1], v[0:1], 0, s[28:29]
	v_lshl_add_u64 v[0:1], v[0:1], 0, v[12:13]
	v_add_u32_e32 v12, v95, v154
	ds_read_b128 v[8:11], v12
	s_waitcnt lgkmcnt(0)
	v_mfma_f32_16x16x32_bf16 v[4:7], v[4:7], v[8:11], 0
	ds_read_b128 v[8:11], v112 offset:36864
	ds_read_b128 v[136:139], v12 offset:64
	s_waitcnt lgkmcnt(0)
	v_mfma_f32_16x16x32_bf16 v[4:7], v[8:11], v[136:139], v[4:7]
	ds_read_b128 v[8:11], v113 offset:36864
	ds_read_b128 v[136:139], v12 offset:128
	s_waitcnt lgkmcnt(0)
	v_mfma_f32_16x16x32_bf16 v[4:7], v[8:11], v[136:139], v[4:7]
	ds_read_b128 v[8:11], v114 offset:36864
	ds_read_b128 v[136:139], v12 offset:192
	s_waitcnt lgkmcnt(0)
	v_mfma_f32_16x16x32_bf16 v[4:7], v[8:11], v[136:139], v[4:7]
	ds_read_b128 v[8:11], v115 offset:36864
	ds_read_b128 v[136:139], v12 offset:256
	s_waitcnt lgkmcnt(0)
	v_mfma_f32_16x16x32_bf16 v[4:7], v[8:11], v[136:139], v[4:7]
	s_nop 7
	v_mul_f32_e32 v4, v17, v4
	v_mul_f32_e32 v5, v17, v5
	v_cvt_pk_bf16_f32 v4, v4, v5
	v_mul_f32_e32 v5, v17, v6
	v_mul_f32_e32 v6, v17, v7
	v_cvt_pk_bf16_f32 v5, v5, v6
	global_store_dwordx2 v[0:1], v[4:5], off
	ds_read_b128 v[4:7], v116 offset:47360
	ds_read_b128 v[8:11], v12
	s_waitcnt lgkmcnt(0)
	v_mfma_f32_16x16x32_bf16 v[4:7], v[4:7], v[8:11], 0
	ds_read_b128 v[8:11], v117 offset:47360
	ds_read_b128 v[136:139], v12 offset:64
	s_waitcnt lgkmcnt(0)
	v_mfma_f32_16x16x32_bf16 v[4:7], v[8:11], v[136:139], v[4:7]
	ds_read_b128 v[8:11], v118 offset:47360
	ds_read_b128 v[136:139], v12 offset:128
	s_waitcnt lgkmcnt(0)
	v_mfma_f32_16x16x32_bf16 v[4:7], v[8:11], v[136:139], v[4:7]
	ds_read_b128 v[8:11], v119 offset:47360
	ds_read_b128 v[136:139], v12 offset:192
	s_waitcnt lgkmcnt(0)
	v_mfma_f32_16x16x32_bf16 v[4:7], v[8:11], v[136:139], v[4:7]
	ds_read_b128 v[8:11], v120 offset:47360
	ds_read_b128 v[136:139], v12 offset:256
	s_waitcnt lgkmcnt(0)
	v_mfma_f32_16x16x32_bf16 v[4:7], v[8:11], v[136:139], v[4:7]
	s_nop 7
	v_mul_f32_e32 v4, v17, v4
	v_mul_f32_e32 v5, v17, v5
	v_cvt_pk_bf16_f32 v4, v4, v5
	v_mul_f32_e32 v5, v17, v6
	v_mul_f32_e32 v6, v17, v7
	v_cvt_pk_bf16_f32 v5, v5, v6
	global_store_dwordx2 v[0:1], v[4:5], off offset:32
	ds_read_b128 v[4:7], v121 offset:57856
	ds_read_b128 v[8:11], v12
	s_waitcnt lgkmcnt(0)
	v_mfma_f32_16x16x32_bf16 v[4:7], v[4:7], v[8:11], 0
	ds_read_b128 v[8:11], v122 offset:57856
	ds_read_b128 v[136:139], v12 offset:64
	s_waitcnt lgkmcnt(0)
	v_mfma_f32_16x16x32_bf16 v[4:7], v[8:11], v[136:139], v[4:7]
	ds_read_b128 v[8:11], v123 offset:57856
	ds_read_b128 v[136:139], v12 offset:128
	s_waitcnt lgkmcnt(0)
	v_mfma_f32_16x16x32_bf16 v[4:7], v[8:11], v[136:139], v[4:7]
	ds_read_b128 v[8:11], v124 offset:57856
	ds_read_b128 v[136:139], v12 offset:192
	s_waitcnt lgkmcnt(0)
	v_mfma_f32_16x16x32_bf16 v[4:7], v[8:11], v[136:139], v[4:7]
	ds_read_b128 v[8:11], v125 offset:57856
	ds_read_b128 v[136:139], v12 offset:256
	s_waitcnt lgkmcnt(0)
	v_mfma_f32_16x16x32_bf16 v[4:7], v[8:11], v[136:139], v[4:7]
	s_nop 7
	v_mul_f32_e32 v4, v17, v4
	v_mul_f32_e32 v5, v17, v5
	v_cvt_pk_bf16_f32 v4, v4, v5
	v_mul_f32_e32 v5, v17, v6
	v_mul_f32_e32 v6, v17, v7
	v_cvt_pk_bf16_f32 v5, v5, v6
	global_store_dwordx2 v[0:1], v[4:5], off offset:64
	ds_read_b128 v[4:7], v126 offset:36864
	ds_read_b128 v[8:11], v12
	s_waitcnt lgkmcnt(0)
	v_mfma_f32_16x16x32_bf16 v[4:7], v[4:7], v[8:11], 0
	ds_read_b128 v[8:11], v127 offset:36864
	ds_read_b128 v[136:139], v12 offset:64
	s_waitcnt lgkmcnt(0)
	v_mfma_f32_16x16x32_bf16 v[4:7], v[8:11], v[136:139], v[4:7]
	ds_read_b128 v[8:11], v130 offset:36864
	ds_read_b128 v[136:139], v12 offset:128
	s_waitcnt lgkmcnt(0)
	v_mfma_f32_16x16x32_bf16 v[4:7], v[8:11], v[136:139], v[4:7]
	ds_read_b128 v[8:11], v131 offset:36864
	ds_read_b128 v[136:139], v12 offset:192
	s_waitcnt lgkmcnt(0)
	v_mfma_f32_16x16x32_bf16 v[4:7], v[8:11], v[136:139], v[4:7]
	ds_read_b128 v[8:11], v132 offset:36864
	ds_read_b128 v[136:139], v12 offset:256
	s_waitcnt lgkmcnt(0)
	v_mfma_f32_16x16x32_bf16 v[4:7], v[8:11], v[136:139], v[4:7]
	s_nop 7
	v_mul_f32_e32 v4, v17, v4
	v_mul_f32_e32 v5, v17, v5
	v_cvt_pk_bf16_f32 v4, v4, v5
	v_mul_f32_e32 v5, v17, v6
	v_mul_f32_e32 v6, v17, v7
	v_cvt_pk_bf16_f32 v5, v5, v6
	global_store_dwordx2 v[0:1], v[4:5], off offset:96
	s_and_saveexec_b64 s[80:81], s[72:73]
	s_cbranch_execz .LBB0_632
	s_mov_b32 s4, 0x800000
	v_cmp_gt_f32_e32 vcc, s4, v3
	s_mov_b32 s4, 0x3f317217
	s_ashr_i32 s79, s78, 31
	v_cndmask_b32_e64 v0, 0, 32, vcc
	v_ldexp_f32 v0, v3, v0
	v_log_f32_e32 v0, v0
	v_cndmask_b32_e32 v1, 0, v135, vcc
	s_lshl_b32 s28, s77, 2
	v_mul_f32_e32 v3, 0x3f317217, v0
	v_fma_f32 v3, v0, s4, -v3
	v_fmac_f32_e32 v3, 0x3377d1cf, v0
	s_mov_b32 s4, 0x7f800000
	v_fmac_f32_e32 v3, 0x3f317217, v0
	v_cmp_lt_f32_e64 vcc, |v0|, s4
	s_nop 1
	v_cndmask_b32_e32 v0, v0, v3, vcc
	v_sub_f32_e32 v0, v0, v1
	v_add_f32_e32 v4, v2, v0
	v_mad_u64_u32 v[0:1], s[6:7], v18, 48, s[38:39]
	v_mov_b32_e32 v2, v1
	v_mad_u64_u32 v[2:3], s[6:7], v19, 48, v[2:3]
	v_mov_b32_e32 v1, v2
	v_lshl_add_u64 v[0:1], s[78:79], 2, v[0:1]
	v_lshl_add_u64 v[0:1], v[0:1], 0, s[28:29]
	global_store_dword v[0:1], v4, off
	s_branch .LBB0_632
